# saddr_form_stage_loads_up_loop
# baseline (speedup 1.0000x reference)
.LBB0_787:
	s_add_u32 s34, s8, 0x100
	s_addc_u32 s35, s9, 0
	s_and_b64 s[36:37], s[36:37], exec
	s_cselect_b32 s39, s64, s35
	s_cselect_b32 s38, s65, s34
	s_cselect_b32 s37, s25, s69
	s_cselect_b32 s36, s66, s68
	s_add_i32 s71, 0, 0x10000
	v_add_u32_e32 v0, s71, v228
	s_add_i32 s74, 0, 0x14000
	ds_read_b128 v[130:133], v0
	ds_read_b128 v[134:137], v0 offset:1024
	ds_read_b128 v[138:141], v0 offset:2048
	ds_read_b128 v[154:157], v0 offset:3072
	v_add_u32_e32 v0, s74, v228
	ds_read_b128 v[166:169], v0
	ds_read_b128 v[170:173], v0 offset:1024
	ds_read_b128 v[174:177], v0 offset:2048
	ds_read_b128 v[178:181], v0 offset:3072
	v_lshl_add_u64 v[158:159], s[8:9], 0, v[150:151]
	s_add_i32 m0, s52, 0xc000
	ds_read_b128 v[182:185], v233
	ds_read_b128 v[186:189], v233 offset:1024
	ds_read_b128 v[190:193], v233 offset:2048
	ds_read_b128 v[194:197], v233 offset:3072
	ds_read_b128 v[198:201], v233 offset:4096
	ds_read_b128 v[202:205], v233 offset:5120
	ds_read_b128 v[206:209], v233 offset:6144
	ds_read_b128 v[210:213], v233 offset:7168
	global_load_lds_dwordx4 v150, s[8:9]
	v_lshl_add_u64 v[158:159], s[8:9], 0, v[152:153]
	s_add_i32 m0, s52, 0xe000
	s_nop 0
	global_load_lds_dwordx4 v152, s[8:9]
	s_waitcnt vmcnt(8)
	s_waitcnt lgkmcnt(0)
	s_barrier
	s_setprio 1
	s_waitcnt lgkmcnt(0)
	v_mfma_f32_16x16x32_bf16 v[118:121], v[130:133], v[182:185], v[118:121]
	v_mfma_f32_16x16x32_bf16 v[54:57], v[138:141], v[182:185], v[54:57]
	v_mfma_f32_16x16x32_bf16 v[114:117], v[130:133], v[190:193], v[114:117]
	v_mfma_f32_16x16x32_bf16 v[50:53], v[138:141], v[190:193], v[50:53]
	v_mfma_f32_16x16x32_bf16 v[126:129], v[130:133], v[198:201], v[126:129]
	v_mfma_f32_16x16x32_bf16 v[62:65], v[138:141], v[198:201], v[62:65]
	v_mfma_f32_16x16x32_bf16 v[122:125], v[130:133], v[206:209], v[122:125]
	v_mfma_f32_16x16x32_bf16 v[58:61], v[138:141], v[206:209], v[58:61]
	v_mfma_f32_16x16x32_bf16 v[118:121], v[134:137], v[186:189], v[118:121]
	v_mfma_f32_16x16x32_bf16 v[54:57], v[154:157], v[186:189], v[54:57]
	v_mfma_f32_16x16x32_bf16 v[114:117], v[134:137], v[194:197], v[114:117]
	v_mfma_f32_16x16x32_bf16 v[50:53], v[154:157], v[194:197], v[50:53]
	v_mfma_f32_16x16x32_bf16 v[126:129], v[134:137], v[202:205], v[126:129]
	v_mfma_f32_16x16x32_bf16 v[62:65], v[154:157], v[202:205], v[62:65]
	v_mfma_f32_16x16x32_bf16 v[122:125], v[134:137], v[210:213], v[122:125]
	v_mfma_f32_16x16x32_bf16 v[58:61], v[154:157], v[210:213], v[58:61]
	s_setprio 0
	s_setprio 1
	v_mfma_f32_16x16x32_bf16 v[102:105], v[166:169], v[182:185], v[102:105]
	v_mfma_f32_16x16x32_bf16 v[38:41], v[174:177], v[182:185], v[38:41]
	v_mfma_f32_16x16x32_bf16 v[98:101], v[166:169], v[190:193], v[98:101]
	v_mfma_f32_16x16x32_bf16 v[34:37], v[174:177], v[190:193], v[34:37]
	v_mfma_f32_16x16x32_bf16 v[110:113], v[166:169], v[198:201], v[110:113]
	v_mfma_f32_16x16x32_bf16 v[46:49], v[174:177], v[198:201], v[46:49]
	v_mfma_f32_16x16x32_bf16 v[106:109], v[166:169], v[206:209], v[106:109]
	v_mfma_f32_16x16x32_bf16 v[42:45], v[174:177], v[206:209], v[42:45]
	v_mfma_f32_16x16x32_bf16 v[102:105], v[170:173], v[186:189], v[102:105]
	v_mfma_f32_16x16x32_bf16 v[38:41], v[178:181], v[186:189], v[38:41]
	v_mfma_f32_16x16x32_bf16 v[98:101], v[170:173], v[194:197], v[98:101]
	v_mfma_f32_16x16x32_bf16 v[34:37], v[178:181], v[194:197], v[34:37]
	v_mfma_f32_16x16x32_bf16 v[110:113], v[170:173], v[202:205], v[110:113]
	v_mfma_f32_16x16x32_bf16 v[46:49], v[178:181], v[202:205], v[46:49]
	v_mfma_f32_16x16x32_bf16 v[106:109], v[170:173], v[210:213], v[106:109]
	v_mfma_f32_16x16x32_bf16 v[42:45], v[178:181], v[210:213], v[42:45]
	s_setprio 0
	s_barrier
	s_add_i32 s8, s71, s51
	v_lshl_add_u64 v[158:159], s[36:37], 0, v[144:145]
	s_mov_b32 m0, s8
	ds_read_b128 v[182:185], v233 offset:16384
	ds_read_b128 v[186:189], v233 offset:17408
	ds_read_b128 v[190:193], v233 offset:18432
	ds_read_b128 v[194:197], v233 offset:19456
	ds_read_b128 v[198:201], v233 offset:20480
	ds_read_b128 v[202:205], v233 offset:21504
	ds_read_b128 v[206:209], v233 offset:22528
	ds_read_b128 v[210:213], v233 offset:23552
	global_load_lds_dwordx4 v144, s[36:37]
	s_add_i32 m0, s8, 0x2000
	s_add_u32 s8, s36, 0x40000
	v_lshl_add_u64 v[162:163], s[36:37], 0, v[148:149]
	s_addc_u32 s9, s37, 0
	s_add_i32 s71, s74, s51
	global_load_lds_dwordx4 v148, s[36:37]
	v_lshl_add_u64 v[214:215], s[8:9], 0, v[144:145]
	s_mov_b32 m0, s71
	v_lshl_add_u64 v[216:217], s[38:39], 0, v[146:147]
	global_load_lds_dwordx4 v144, s[8:9]
	v_lshl_add_u64 v[214:215], s[8:9], 0, v[148:149]
	s_add_i32 m0, s71, 0x2000
	s_nop 0
	global_load_lds_dwordx4 v148, s[8:9]
	v_lshl_add_u64 v[214:215], s[38:39], 0, v[142:143]
	s_mov_b32 m0, s52
	s_nop 0
	global_load_lds_dwordx4 v142, s[38:39]
	s_mov_b32 m0, s53
	s_nop 0
	global_load_lds_dwordx4 v146, s[38:39]
	s_waitcnt vmcnt(8)
	s_waitcnt lgkmcnt(0)
	s_barrier
	s_setprio 1
	s_waitcnt lgkmcnt(0)
	v_mfma_f32_16x16x32_bf16 v[86:89], v[130:133], v[182:185], v[86:89]
	v_mfma_f32_16x16x32_bf16 v[22:25], v[138:141], v[182:185], v[22:25]
	v_mfma_f32_16x16x32_bf16 v[82:85], v[130:133], v[190:193], v[82:85]
	v_mfma_f32_16x16x32_bf16 v[18:21], v[138:141], v[190:193], v[18:21]
	v_mfma_f32_16x16x32_bf16 v[94:97], v[130:133], v[198:201], v[94:97]
	v_mfma_f32_16x16x32_bf16 v[30:33], v[138:141], v[198:201], v[30:33]
	v_mfma_f32_16x16x32_bf16 v[90:93], v[130:133], v[206:209], v[90:93]
	v_mfma_f32_16x16x32_bf16 v[26:29], v[138:141], v[206:209], v[26:29]
	v_mfma_f32_16x16x32_bf16 v[86:89], v[134:137], v[186:189], v[86:89]
	v_mfma_f32_16x16x32_bf16 v[22:25], v[154:157], v[186:189], v[22:25]
	v_mfma_f32_16x16x32_bf16 v[82:85], v[134:137], v[194:197], v[82:85]
	v_mfma_f32_16x16x32_bf16 v[18:21], v[154:157], v[194:197], v[18:21]
	v_mfma_f32_16x16x32_bf16 v[94:97], v[134:137], v[202:205], v[94:97]
	v_mfma_f32_16x16x32_bf16 v[30:33], v[154:157], v[202:205], v[30:33]
	v_mfma_f32_16x16x32_bf16 v[90:93], v[134:137], v[210:213], v[90:93]
	v_mfma_f32_16x16x32_bf16 v[26:29], v[154:157], v[210:213], v[26:29]
	s_setprio 0
	s_setprio 1
	v_mfma_f32_16x16x32_bf16 v[70:73], v[166:169], v[182:185], v[70:73]
	v_mfma_f32_16x16x32_bf16 v[6:9], v[174:177], v[182:185], v[6:9]
	v_mfma_f32_16x16x32_bf16 v[66:69], v[166:169], v[190:193], v[66:69]
	v_mfma_f32_16x16x32_bf16 v[2:5], v[174:177], v[190:193], v[2:5]
	v_mfma_f32_16x16x32_bf16 v[78:81], v[166:169], v[198:201], v[78:81]
	v_mfma_f32_16x16x32_bf16 v[14:17], v[174:177], v[198:201], v[14:17]
	v_mfma_f32_16x16x32_bf16 v[74:77], v[166:169], v[206:209], v[74:77]
	v_mfma_f32_16x16x32_bf16 v[10:13], v[174:177], v[206:209], v[10:13]
	v_mfma_f32_16x16x32_bf16 v[70:73], v[170:173], v[186:189], v[70:73]
	v_mfma_f32_16x16x32_bf16 v[6:9], v[178:181], v[186:189], v[6:9]
	v_mfma_f32_16x16x32_bf16 v[66:69], v[170:173], v[194:197], v[66:69]
	v_mfma_f32_16x16x32_bf16 v[2:5], v[178:181], v[194:197], v[2:5]
	v_mfma_f32_16x16x32_bf16 v[78:81], v[170:173], v[202:205], v[78:81]
	v_mfma_f32_16x16x32_bf16 v[14:17], v[178:181], v[202:205], v[14:17]
	v_mfma_f32_16x16x32_bf16 v[74:77], v[170:173], v[210:213], v[74:77]
	v_mfma_f32_16x16x32_bf16 v[10:13], v[178:181], v[210:213], v[10:13]
	s_setprio 0
	s_barrier
	s_add_i32 s71, 0, 0x18000
	v_add_u32_e32 v0, s71, v228
	s_add_i32 s74, 0, 0x1c000
	ds_read_b128 v[130:133], v0
	ds_read_b128 v[134:137], v0 offset:1024
	ds_read_b128 v[138:141], v0 offset:2048
	ds_read_b128 v[154:157], v0 offset:3072
	v_add_u32_e32 v0, s74, v228
	ds_read_b128 v[166:169], v0
	ds_read_b128 v[170:173], v0 offset:1024
	ds_read_b128 v[174:177], v0 offset:2048
	ds_read_b128 v[178:181], v0 offset:3072
	s_add_u32 s8, s38, 0x40000
	s_addc_u32 s9, s39, 0
	s_mov_b32 m0, s54
	v_lshl_add_u64 v[218:219], s[8:9], 0, v[142:143]
	ds_read_b128 v[182:185], v233 offset:32768
	ds_read_b128 v[186:189], v233 offset:33792
	ds_read_b128 v[190:193], v233 offset:34816
	ds_read_b128 v[194:197], v233 offset:35840
	ds_read_b128 v[198:201], v233 offset:36864
	ds_read_b128 v[202:205], v233 offset:37888
	ds_read_b128 v[206:209], v233 offset:38912
	ds_read_b128 v[210:213], v233 offset:39936
	global_load_lds_dwordx4 v142, s[8:9]
	v_lshl_add_u64 v[218:219], s[8:9], 0, v[146:147]
	s_mov_b32 m0, s55
	s_nop 0
	global_load_lds_dwordx4 v146, s[8:9]
	s_waitcnt vmcnt(8)
	s_waitcnt lgkmcnt(0)
	s_barrier
	s_setprio 1
	s_waitcnt lgkmcnt(0)
	v_mfma_f32_16x16x32_bf16 v[118:121], v[130:133], v[182:185], v[118:121]
	v_mfma_f32_16x16x32_bf16 v[54:57], v[138:141], v[182:185], v[54:57]
	v_mfma_f32_16x16x32_bf16 v[114:117], v[130:133], v[190:193], v[114:117]
	v_mfma_f32_16x16x32_bf16 v[50:53], v[138:141], v[190:193], v[50:53]
	v_mfma_f32_16x16x32_bf16 v[126:129], v[130:133], v[198:201], v[126:129]
	v_mfma_f32_16x16x32_bf16 v[62:65], v[138:141], v[198:201], v[62:65]
	v_mfma_f32_16x16x32_bf16 v[122:125], v[130:133], v[206:209], v[122:125]
	v_mfma_f32_16x16x32_bf16 v[58:61], v[138:141], v[206:209], v[58:61]
	v_mfma_f32_16x16x32_bf16 v[118:121], v[134:137], v[186:189], v[118:121]
	v_mfma_f32_16x16x32_bf16 v[54:57], v[154:157], v[186:189], v[54:57]
	v_mfma_f32_16x16x32_bf16 v[114:117], v[134:137], v[194:197], v[114:117]
	v_mfma_f32_16x16x32_bf16 v[50:53], v[154:157], v[194:197], v[50:53]
	v_mfma_f32_16x16x32_bf16 v[126:129], v[134:137], v[202:205], v[126:129]
	v_mfma_f32_16x16x32_bf16 v[62:65], v[154:157], v[202:205], v[62:65]
	v_mfma_f32_16x16x32_bf16 v[122:125], v[134:137], v[210:213], v[122:125]
	v_mfma_f32_16x16x32_bf16 v[58:61], v[154:157], v[210:213], v[58:61]
	s_setprio 0
	s_setprio 1
	v_mfma_f32_16x16x32_bf16 v[102:105], v[166:169], v[182:185], v[102:105]
	v_mfma_f32_16x16x32_bf16 v[38:41], v[174:177], v[182:185], v[38:41]
	v_mfma_f32_16x16x32_bf16 v[98:101], v[166:169], v[190:193], v[98:101]
	v_mfma_f32_16x16x32_bf16 v[34:37], v[174:177], v[190:193], v[34:37]
	v_mfma_f32_16x16x32_bf16 v[110:113], v[166:169], v[198:201], v[110:113]
	v_mfma_f32_16x16x32_bf16 v[46:49], v[174:177], v[198:201], v[46:49]
	v_mfma_f32_16x16x32_bf16 v[106:109], v[166:169], v[206:209], v[106:109]
	v_mfma_f32_16x16x32_bf16 v[42:45], v[174:177], v[206:209], v[42:45]
	v_mfma_f32_16x16x32_bf16 v[102:105], v[170:173], v[186:189], v[102:105]
	v_mfma_f32_16x16x32_bf16 v[38:41], v[178:181], v[186:189], v[38:41]
	v_mfma_f32_16x16x32_bf16 v[98:101], v[170:173], v[194:197], v[98:101]
	v_mfma_f32_16x16x32_bf16 v[34:37], v[178:181], v[194:197], v[34:37]
	v_mfma_f32_16x16x32_bf16 v[110:113], v[170:173], v[202:205], v[110:113]
	v_mfma_f32_16x16x32_bf16 v[46:49], v[178:181], v[202:205], v[46:49]
	v_mfma_f32_16x16x32_bf16 v[106:109], v[170:173], v[210:213], v[106:109]
	v_mfma_f32_16x16x32_bf16 v[42:45], v[178:181], v[210:213], v[42:45]
	s_setprio 0
	s_barrier
	s_add_i32 s8, s71, s51
	s_add_u32 s98, s36, 0x80
	s_addc_u32 s99, s37, 0
	s_add_u32 s100, s38, 0x80
	s_addc_u32 s101, s39, 0
	v_lshl_add_u64 v[158:159], v[158:159], 0, s[82:83]
	s_mov_b32 m0, s8
	ds_read_b128 v[182:185], v233 offset:49152
	ds_read_b128 v[186:189], v233 offset:50176
	ds_read_b128 v[190:193], v233 offset:51200
	ds_read_b128 v[194:197], v233 offset:52224
	ds_read_b128 v[198:201], v233 offset:53248
	ds_read_b128 v[202:205], v233 offset:54272
	ds_read_b128 v[206:209], v233 offset:55296
	ds_read_b128 v[210:213], v233 offset:56320
	global_load_lds_dwordx4 v144, s[98:99]
	s_add_i32 m0, s8, 0x2000
	s_add_u32 s8, s36, 0x40080
	v_lshl_add_u64 v[158:159], v[162:163], 0, s[82:83]
	s_addc_u32 s9, s37, 0
	s_add_i32 s36, s74, s51
	global_load_lds_dwordx4 v148, s[98:99]
	v_lshl_add_u64 v[158:159], s[8:9], 0, v[144:145]
	s_mov_b32 m0, s36
	s_nop 0
	global_load_lds_dwordx4 v144, s[8:9]
	v_lshl_add_u64 v[158:159], s[8:9], 0, v[148:149]
	s_add_i32 m0, s36, 0x2000
	s_nop 0
	global_load_lds_dwordx4 v148, s[8:9]
	v_lshl_add_u64 v[158:159], v[214:215], 0, s[82:83]
	s_mov_b32 m0, s58
	s_nop 0
	global_load_lds_dwordx4 v142, s[100:101]
	v_lshl_add_u64 v[158:159], v[216:217], 0, s[82:83]
	s_mov_b32 m0, s59
	s_nop 0
	global_load_lds_dwordx4 v146, s[100:101]
	s_waitcnt vmcnt(8)
	s_waitcnt lgkmcnt(0)
	s_barrier
	s_setprio 1
	s_waitcnt lgkmcnt(0)
	v_mfma_f32_16x16x32_bf16 v[86:89], v[130:133], v[182:185], v[86:89]
	v_mfma_f32_16x16x32_bf16 v[22:25], v[138:141], v[182:185], v[22:25]
	v_mfma_f32_16x16x32_bf16 v[82:85], v[130:133], v[190:193], v[82:85]
	v_mfma_f32_16x16x32_bf16 v[18:21], v[138:141], v[190:193], v[18:21]
	v_mfma_f32_16x16x32_bf16 v[94:97], v[130:133], v[198:201], v[94:97]
	v_mfma_f32_16x16x32_bf16 v[30:33], v[138:141], v[198:201], v[30:33]
	v_mfma_f32_16x16x32_bf16 v[90:93], v[130:133], v[206:209], v[90:93]
	v_mfma_f32_16x16x32_bf16 v[26:29], v[138:141], v[206:209], v[26:29]
	v_mfma_f32_16x16x32_bf16 v[86:89], v[134:137], v[186:189], v[86:89]
	v_mfma_f32_16x16x32_bf16 v[22:25], v[154:157], v[186:189], v[22:25]
	v_mfma_f32_16x16x32_bf16 v[82:85], v[134:137], v[194:197], v[82:85]
	v_mfma_f32_16x16x32_bf16 v[18:21], v[154:157], v[194:197], v[18:21]
	v_mfma_f32_16x16x32_bf16 v[94:97], v[134:137], v[202:205], v[94:97]
	v_mfma_f32_16x16x32_bf16 v[30:33], v[154:157], v[202:205], v[30:33]
	v_mfma_f32_16x16x32_bf16 v[90:93], v[134:137], v[210:213], v[90:93]
	v_mfma_f32_16x16x32_bf16 v[26:29], v[154:157], v[210:213], v[26:29]
	s_setprio 0
	s_setprio 1
	v_mfma_f32_16x16x32_bf16 v[70:73], v[166:169], v[182:185], v[70:73]
	v_mfma_f32_16x16x32_bf16 v[6:9], v[174:177], v[182:185], v[6:9]
	v_mfma_f32_16x16x32_bf16 v[66:69], v[166:169], v[190:193], v[66:69]
	v_mfma_f32_16x16x32_bf16 v[2:5], v[174:177], v[190:193], v[2:5]
	v_mfma_f32_16x16x32_bf16 v[78:81], v[166:169], v[198:201], v[78:81]
	v_mfma_f32_16x16x32_bf16 v[14:17], v[174:177], v[198:201], v[14:17]
	v_mfma_f32_16x16x32_bf16 v[74:77], v[166:169], v[206:209], v[74:77]
	v_mfma_f32_16x16x32_bf16 v[10:13], v[174:177], v[206:209], v[10:13]
	v_mfma_f32_16x16x32_bf16 v[70:73], v[170:173], v[186:189], v[70:73]
	v_mfma_f32_16x16x32_bf16 v[6:9], v[178:181], v[186:189], v[6:9]
	v_mfma_f32_16x16x32_bf16 v[66:69], v[170:173], v[194:197], v[66:69]
	v_mfma_f32_16x16x32_bf16 v[2:5], v[178:181], v[194:197], v[2:5]
	v_mfma_f32_16x16x32_bf16 v[78:81], v[170:173], v[202:205], v[78:81]
	v_mfma_f32_16x16x32_bf16 v[14:17], v[178:181], v[202:205], v[14:17]
	v_mfma_f32_16x16x32_bf16 v[74:77], v[170:173], v[210:213], v[74:77]
	v_mfma_f32_16x16x32_bf16 v[10:13], v[178:181], v[210:213], v[10:13]
	s_setprio 0
	s_barrier
	s_add_i32 s70, s70, 2
	s_add_u32 s68, s68, 0x100
	s_addc_u32 s69, s69, 0
	s_cmp_gt_u32 s70, 13
	s_cbranch_scc1 .LBB0_789
	s_mov_b64 s[8:9], s[34:35]
	s_branch .LBB0_782
